# attention: odd grid-row quarters walk their query rows downwards so neighbouring quarters on one XCD stream shared halo K/V rows at the same time (L2 reuse)
# baseline (speedup 1.0000x reference)
; __global__ void __launch_bounds__(NTHREADS, 2) mega(Args args) {
;     ...
; #pragma unroll 1
;                     for (int rd = 0; rd < 4; ++rd) attn_unit<true>(Qb, KTp, VTp, Ob, lds, b, h, 8 * qr + 2 * rd + (wave >> 2), wave & 3, 0, lane);
.LBB9_672:
	s_or_b64 exec, exec, s[50:51]
	s_and_b32 s5, s69, 3
	s_lshl_b32 s34, s5, 9
	s_lshl_b32 s5, s5, 3
	s_lshl_b32 s4, s4, 11
	s_add_i32 s50, s66, s5
	s_lshl_b32 s48, s72, 8
	v_add_u32_e32 v157, s4, v167
	s_or_b32 s4, s34, s4
	s_sub_i32 s51, s68, s5
	s_lshl_b32 s33, s72, 7
	v_lshl_add_u64 v[158:159], v[144:145], 0, s[48:49]
	v_lshl_add_u64 v[160:161], v[150:151], 0, s[48:49]
	v_add_u32_e32 v162, s4, v193
	s_mov_b32 s48, 0
	s_mov_b32 s52, s50
	s_and_b32 s82, s69, 1
	s_mov_b32 s80, 2
	s_cmp_eq_u32 s82, 0
	s_cbranch_scc1 .Lrev_done
	s_mov_b32 s80, -2
	s_add_i32 s52, s52, 6
	s_add_i32 s51, s51, -6
	v_add_u32_e32 v162, 0x180, v162
.Lrev_done:
	s_waitcnt lgkmcnt(0)
	s_barrier
	s_branch .LBB9_674

; #define LAS __attribute__((address_space(3)))
; template <bool LOCAL>
; __device__ __forceinline__ void attn_unit(const bf16_t* Q, const bf16_t* KT, const bf16_t* VT, bf16_t* O, LAS unsigned char* lds, int b, int h, int r, int w, int tq, int lane) {
;     ...
;     {
;         const LAS unsigned char* vl = lds + 65536 + g * 2048 + q * 16;
; #pragma unroll
;         for (int p = 0; p < 8; ++p)
; #pragma unroll
;             for (int df = 0; df < 8; ++df) o[df] = __builtin_amdgcn_mfma_f32_16x16x32_bf16(*(const LAS bf16x8*)(vl + p * 8192 + df * 256), pb[CP + p], o[df], 0, 0, 0);
;     }
.Lrg_v_B_end:
.Lrg_v_done:
	s_barrier
	v_mov_b32_e32 v222, v234
	v_mov_b32_e32 v223, v235
	s_lshl_b32 s55, s57, 10
	s_add_i32 m0, s55, 0
	s_nop 0
	global_load_lds_dwordx4 v[222:223], off
	v_add_co_u32_e32 v222, vcc, 0x20000, v222
	s_nop 1
	v_addc_co_u32_e32 v223, vcc, 0, v223, vcc
	s_add_i32 m0, s55, 8192
	s_nop 0
	global_load_lds_dwordx4 v[222:223], off
	v_add_co_u32_e32 v222, vcc, 0x20000, v222
	s_nop 1
	v_addc_co_u32_e32 v223, vcc, 0, v223, vcc
	s_add_i32 m0, s55, 16384
	s_nop 0
	global_load_lds_dwordx4 v[222:223], off
	v_add_co_u32_e32 v222, vcc, 0x20000, v222
	s_nop 1
	v_addc_co_u32_e32 v223, vcc, 0, v223, vcc
	s_add_i32 m0, s55, 24576
	s_nop 0
	global_load_lds_dwordx4 v[222:223], off
	v_add_co_u32_e32 v222, vcc, 0x20000, v222
	s_nop 1
	v_addc_co_u32_e32 v223, vcc, 0, v223, vcc
	s_add_i32 m0, s55, 32768
	s_nop 0
	global_load_lds_dwordx4 v[222:223], off
	v_add_co_u32_e32 v222, vcc, 0x20000, v222
	s_nop 1
	v_addc_co_u32_e32 v223, vcc, 0, v223, vcc
	s_add_i32 m0, s55, 40960
	s_nop 0
	global_load_lds_dwordx4 v[222:223], off
	v_add_co_u32_e32 v222, vcc, 0x20000, v222
	s_nop 1
	v_addc_co_u32_e32 v223, vcc, 0, v223, vcc
	s_add_i32 m0, s55, 49152
	s_nop 0
	global_load_lds_dwordx4 v[222:223], off
	v_add_co_u32_e32 v222, vcc, 0x20000, v222
	s_nop 1
	v_addc_co_u32_e32 v223, vcc, 0, v223, vcc
	s_add_i32 m0, s55, 57344
	s_nop 0
	global_load_lds_dwordx4 v[222:223], off
	s_waitcnt lgkmcnt(0)
	s_add_i32 s48, s48, 2
	s_add_i32 s52, s52, s80
	s_sub_i32 s51, s51, s80
	s_lshl_b32 s82, s80, 6
	v_add_u32_e32 v162, s82, v162
	s_cmp_eq_u32 s48, 8
	ds_read_b128 v[200:203], v178
	ds_read_b128 v[204:207], v178 offset:256
	ds_read_b128 v[208:211], v178 offset:512
	ds_read_b128 v[212:215], v178 offset:768
	ds_read_b128 v[216:219], v178 offset:1024
	ds_read_b128 v[220:223], v178 offset:1280
	ds_read_b128 v[224:227], v178 offset:1536
	ds_read_b128 v[228:231], v178 offset:1792
	s_waitcnt lgkmcnt(7)
	v_mfma_f32_16x16x32_bf16 v[22:25], v[200:203], v[98:101], v[22:25]
	ds_read_b128 v[200:203], v178 offset:8192
	s_waitcnt lgkmcnt(7)
	v_mfma_f32_16x16x32_bf16 v[30:33], v[204:207], v[98:101], v[30:33]
	ds_read_b128 v[204:207], v178 offset:8448
	s_waitcnt lgkmcnt(7)
	v_mfma_f32_16x16x32_bf16 v[34:37], v[208:211], v[98:101], v[34:37]
	ds_read_b128 v[208:211], v178 offset:8704
	s_waitcnt lgkmcnt(7)
	v_mfma_f32_16x16x32_bf16 v[38:41], v[212:215], v[98:101], v[38:41]
	ds_read_b128 v[212:215], v178 offset:8960
	s_waitcnt lgkmcnt(7)
	v_mfma_f32_16x16x32_bf16 v[42:45], v[216:219], v[98:101], v[42:45]
	ds_read_b128 v[216:219], v178 offset:9216
	s_waitcnt lgkmcnt(7)
	v_mfma_f32_16x16x32_bf16 v[46:49], v[220:223], v[98:101], v[46:49]
	ds_read_b128 v[220:223], v178 offset:9472
	s_waitcnt lgkmcnt(7)
	v_mfma_f32_16x16x32_bf16 v[50:53], v[224:227], v[98:101], v[50:53]
	ds_read_b128 v[224:227], v178 offset:9728
	s_waitcnt lgkmcnt(7)
	v_mfma_f32_16x16x32_bf16 v[54:57], v[228:231], v[98:101], v[54:57]
	ds_read_b128 v[228:231], v178 offset:9984
	s_waitcnt lgkmcnt(7)
	v_mfma_f32_16x16x32_bf16 v[22:25], v[200:203], v[90:93], v[22:25]
	ds_read_b128 v[200:203], v178 offset:16384
	s_waitcnt lgkmcnt(7)
	v_mfma_f32_16x16x32_bf16 v[30:33], v[204:207], v[90:93], v[30:33]
	ds_read_b128 v[204:207], v178 offset:16640
	s_waitcnt lgkmcnt(7)
	v_mfma_f32_16x16x32_bf16 v[34:37], v[208:211], v[90:93], v[34:37]
	ds_read_b128 v[208:211], v178 offset:16896
	s_waitcnt lgkmcnt(7)
	v_mfma_f32_16x16x32_bf16 v[38:41], v[212:215], v[90:93], v[38:41]
	ds_read_b128 v[212:215], v178 offset:17152
	s_waitcnt lgkmcnt(7)
	v_mfma_f32_16x16x32_bf16 v[42:45], v[216:219], v[90:93], v[42:45]
	ds_read_b128 v[216:219], v178 offset:17408
	s_waitcnt lgkmcnt(7)
	v_mfma_f32_16x16x32_bf16 v[46:49], v[220:223], v[90:93], v[46:49]
	ds_read_b128 v[220:223], v178 offset:17664
	s_waitcnt lgkmcnt(7)
	v_mfma_f32_16x16x32_bf16 v[50:53], v[224:227], v[90:93], v[50:53]
	ds_read_b128 v[224:227], v178 offset:17920
	s_waitcnt lgkmcnt(7)
	v_mfma_f32_16x16x32_bf16 v[54:57], v[228:231], v[90:93], v[54:57]
	ds_read_b128 v[228:231], v178 offset:18176
	s_waitcnt lgkmcnt(7)
	v_mfma_f32_16x16x32_bf16 v[22:25], v[200:203], v[26:29], v[22:25]
	ds_read_b128 v[200:203], v178 offset:24576
	s_waitcnt lgkmcnt(7)
	v_mfma_f32_16x16x32_bf16 v[30:33], v[204:207], v[26:29], v[30:33]
	ds_read_b128 v[204:207], v178 offset:24832
	s_waitcnt lgkmcnt(7)
	v_mfma_f32_16x16x32_bf16 v[34:37], v[208:211], v[26:29], v[34:37]
	ds_read_b128 v[208:211], v178 offset:25088
	s_waitcnt lgkmcnt(7)
	v_mfma_f32_16x16x32_bf16 v[38:41], v[212:215], v[26:29], v[38:41]
	ds_read_b128 v[212:215], v178 offset:25344
	s_waitcnt lgkmcnt(7)
	v_mfma_f32_16x16x32_bf16 v[42:45], v[216:219], v[26:29], v[42:45]
	ds_read_b128 v[216:219], v178 offset:25600
	s_waitcnt lgkmcnt(7)
	v_mfma_f32_16x16x32_bf16 v[46:49], v[220:223], v[26:29], v[46:49]
	ds_read_b128 v[220:223], v178 offset:25856
	s_waitcnt lgkmcnt(7)
	v_mfma_f32_16x16x32_bf16 v[50:53], v[224:227], v[26:29], v[50:53]
	ds_read_b128 v[224:227], v178 offset:26112
	s_waitcnt lgkmcnt(7)
	v_mfma_f32_16x16x32_bf16 v[26:29], v[228:231], v[26:29], v[54:57]
	ds_read_b128 v[228:231], v178 offset:26368
	s_waitcnt lgkmcnt(7)
	v_mfma_f32_16x16x32_bf16 v[22:25], v[200:203], v[10:13], v[22:25]
	ds_read_b128 v[200:203], v178 offset:32768
	s_waitcnt lgkmcnt(7)
	v_mfma_f32_16x16x32_bf16 v[30:33], v[204:207], v[10:13], v[30:33]
	ds_read_b128 v[204:207], v178 offset:33024
	s_waitcnt lgkmcnt(7)
	v_mfma_f32_16x16x32_bf16 v[34:37], v[208:211], v[10:13], v[34:37]
	ds_read_b128 v[208:211], v178 offset:33280
	s_waitcnt lgkmcnt(7)
	v_mfma_f32_16x16x32_bf16 v[38:41], v[212:215], v[10:13], v[38:41]
	ds_read_b128 v[212:215], v178 offset:33536
	s_waitcnt lgkmcnt(7)
; #define LAS __attribute__((address_space(3)))
; __device__ __forceinline__ unsigned cvt_pk_bf16(float lo, float hi) { unsigned r; asm volatile("v_cvt_pk_bf16_f32 %0, %1, %2" : "=v"(r) : "v"(lo), "v"(hi)); return r; }
; template <bool LOCAL>
; __device__ __forceinline__ void attn_unit(const bf16_t* Q, const bf16_t* KT, const bf16_t* VT, bf16_t* O, LAS unsigned char* lds, int b, int h, int r, int w, int tq, int lane) {
;     ...
;     {
;         const LAS unsigned char* vl = lds + 65536 + g * 2048 + q * 16;
; #pragma unroll
;         for (int p = 0; p < 8; ++p)
; #pragma unroll
;             for (int df = 0; df < 8; ++df) o[df] = __builtin_amdgcn_mfma_f32_16x16x32_bf16(*(const LAS bf16x8*)(vl + p * 8192 + df * 256), pb[CP + p], o[df], 0, 0, 0);
;     }
;     const float inv = 1.f / sum;
;     bf16_t* op = O + (size_t)qrow * D + h * HD + 4 * g;
; #pragma unroll
;     for (int df = 0; df < 8; ++df) { u32x2 wv; wv.x = cvt_pk_bf16(o[df][0] * inv, o[df][1] * inv); wv.y = cvt_pk_bf16(o[df][2] * inv, o[df][3] * inv); *(u32x2*)(op + 16 * df) = wv; }
	v_mfma_f32_16x16x32_bf16 v[42:45], v[216:219], v[10:13], v[42:45]
	ds_read_b128 v[216:219], v178 offset:33792
	s_waitcnt lgkmcnt(7)
	v_mfma_f32_16x16x32_bf16 v[46:49], v[220:223], v[10:13], v[46:49]
	ds_read_b128 v[220:223], v178 offset:34048
	s_waitcnt lgkmcnt(7)
	v_mfma_f32_16x16x32_bf16 v[50:53], v[224:227], v[10:13], v[50:53]
	ds_read_b128 v[224:227], v178 offset:34304
	s_waitcnt lgkmcnt(7)
	v_mfma_f32_16x16x32_bf16 v[10:13], v[228:231], v[10:13], v[26:29]
	ds_read_b128 v[228:231], v178 offset:34560
	s_waitcnt lgkmcnt(7)
	v_mfma_f32_16x16x32_bf16 v[22:25], v[200:203], v[2:5], v[22:25]
	ds_read_b128 v[200:203], v178 offset:40960
	s_waitcnt lgkmcnt(7)
	v_mfma_f32_16x16x32_bf16 v[26:29], v[204:207], v[2:5], v[30:33]
	ds_read_b128 v[204:207], v178 offset:41216
	s_waitcnt lgkmcnt(7)
	v_mfma_f32_16x16x32_bf16 v[30:33], v[208:211], v[2:5], v[34:37]
	ds_read_b128 v[208:211], v178 offset:41472
	s_waitcnt lgkmcnt(7)
	v_mfma_f32_16x16x32_bf16 v[34:37], v[212:215], v[2:5], v[38:41]
	ds_read_b128 v[212:215], v178 offset:41728
	s_waitcnt lgkmcnt(7)
	v_mfma_f32_16x16x32_bf16 v[38:41], v[216:219], v[2:5], v[42:45]
	ds_read_b128 v[216:219], v178 offset:41984
	s_waitcnt lgkmcnt(7)
	v_mfma_f32_16x16x32_bf16 v[42:45], v[220:223], v[2:5], v[46:49]
	ds_read_b128 v[220:223], v178 offset:42240
	s_waitcnt lgkmcnt(7)
	v_mfma_f32_16x16x32_bf16 v[46:49], v[224:227], v[2:5], v[50:53]
	ds_read_b128 v[224:227], v178 offset:42496
	s_waitcnt lgkmcnt(7)
	v_mfma_f32_16x16x32_bf16 v[2:5], v[228:231], v[2:5], v[10:13]
	ds_read_b128 v[228:231], v178 offset:42752
	s_waitcnt lgkmcnt(7)
	v_mfma_f32_16x16x32_bf16 v[10:13], v[200:203], v[6:9], v[22:25]
	ds_read_b128 v[200:203], v178 offset:49152
	s_waitcnt lgkmcnt(7)
	v_mfma_f32_16x16x32_bf16 v[22:25], v[204:207], v[6:9], v[26:29]
	ds_read_b128 v[204:207], v178 offset:49408
	s_waitcnt lgkmcnt(7)
	v_mfma_f32_16x16x32_bf16 v[26:29], v[208:211], v[6:9], v[30:33]
	ds_read_b128 v[208:211], v178 offset:49664
	s_waitcnt lgkmcnt(7)
	v_mfma_f32_16x16x32_bf16 v[30:33], v[212:215], v[6:9], v[34:37]
	ds_read_b128 v[212:215], v178 offset:49920
	s_waitcnt lgkmcnt(7)
	v_mfma_f32_16x16x32_bf16 v[34:37], v[216:219], v[6:9], v[38:41]
	ds_read_b128 v[216:219], v178 offset:50176
	s_waitcnt lgkmcnt(7)
	v_mfma_f32_16x16x32_bf16 v[38:41], v[220:223], v[6:9], v[42:45]
	ds_read_b128 v[220:223], v178 offset:50432
	s_waitcnt lgkmcnt(7)
	v_mfma_f32_16x16x32_bf16 v[42:45], v[224:227], v[6:9], v[46:49]
	ds_read_b128 v[224:227], v178 offset:50688
	s_waitcnt lgkmcnt(7)
	v_mfma_f32_16x16x32_bf16 v[2:5], v[228:231], v[6:9], v[2:5]
	ds_read_b128 v[228:231], v178 offset:50944
	s_waitcnt lgkmcnt(7)
	v_mfma_f32_16x16x32_bf16 v[6:9], v[200:203], v[14:17], v[10:13]
	ds_read_b128 v[200:203], v178 offset:57344
	s_waitcnt lgkmcnt(7)
	v_mfma_f32_16x16x32_bf16 v[10:13], v[204:207], v[14:17], v[22:25]
	ds_read_b128 v[204:207], v178 offset:57600
	s_waitcnt lgkmcnt(7)
	v_mfma_f32_16x16x32_bf16 v[22:25], v[208:211], v[14:17], v[26:29]
	ds_read_b128 v[208:211], v178 offset:57856
	s_waitcnt lgkmcnt(7)
	v_mfma_f32_16x16x32_bf16 v[26:29], v[212:215], v[14:17], v[30:33]
	ds_read_b128 v[212:215], v178 offset:58112
	s_waitcnt lgkmcnt(7)
	v_mfma_f32_16x16x32_bf16 v[30:33], v[216:219], v[14:17], v[34:37]
	ds_read_b128 v[216:219], v178 offset:58368
	s_waitcnt lgkmcnt(7)
	v_mfma_f32_16x16x32_bf16 v[34:37], v[220:223], v[14:17], v[38:41]
	ds_read_b128 v[220:223], v178 offset:58624
	s_waitcnt lgkmcnt(7)
	v_mfma_f32_16x16x32_bf16 v[38:41], v[224:227], v[14:17], v[42:45]
	ds_read_b128 v[224:227], v178 offset:58880
	s_waitcnt lgkmcnt(7)
	v_mfma_f32_16x16x32_bf16 v[2:5], v[228:231], v[14:17], v[2:5]
	ds_read_b128 v[228:231], v178 offset:59136
	s_waitcnt lgkmcnt(7)
	v_mfma_f32_16x16x32_bf16 v[6:9], v[200:203], v[18:21], v[6:9]
	s_waitcnt lgkmcnt(6)
	v_mfma_f32_16x16x32_bf16 v[10:13], v[204:207], v[18:21], v[10:13]
	s_waitcnt lgkmcnt(5)
	v_mfma_f32_16x16x32_bf16 v[14:17], v[208:211], v[18:21], v[22:25]
	s_waitcnt lgkmcnt(4)
	v_mfma_f32_16x16x32_bf16 v[22:25], v[212:215], v[18:21], v[26:29]
	s_waitcnt lgkmcnt(3)
	v_mfma_f32_16x16x32_bf16 v[26:29], v[216:219], v[18:21], v[30:33]
	s_waitcnt lgkmcnt(2)
	v_mfma_f32_16x16x32_bf16 v[30:33], v[220:223], v[18:21], v[34:37]
	s_waitcnt lgkmcnt(1)
	v_mfma_f32_16x16x32_bf16 v[34:37], v[224:227], v[18:21], v[38:41]
	s_waitcnt lgkmcnt(0)
	v_mfma_f32_16x16x32_bf16 v[2:5], v[228:231], v[18:21], v[2:5]
	s_nop 7
	v_add_f32_e32 v18, v134, v135
	v_div_scale_f32 v19, s[4:5], v18, v18, 1.0
	v_rcp_f32_e32 v20, v19
	s_nop 0
	v_fma_f32 v21, -v19, v20, 1.0
	v_fmac_f32_e32 v20, v21, v20
	v_div_scale_f32 v21, vcc, 1.0, v18, 1.0
	v_mul_f32_e32 v38, v21, v20
	v_fma_f32 v39, -v19, v38, v21
	v_fmac_f32_e32 v38, v39, v20
	v_fma_f32 v19, -v19, v38, v21
	v_div_fmas_f32 v19, v19, v20, v38
	v_div_fixup_f32 v20, v19, v18, 1.0
	v_mul_f32_e32 v6, v20, v6
	v_mul_f32_e32 v7, v20, v7
	v_cvt_pk_bf16_f32 v6, v6, v7
	v_mul_f32_e32 v7, v20, v8
	v_lshl_add_u64 v[18:19], v[130:131], 1, v[160:161]
	v_mul_f32_e32 v8, v20, v9
	v_cvt_pk_bf16_f32 v7, v7, v8
	global_store_dwordx2 v[18:19], v[6:7], off
	v_mul_f32_e32 v6, v20, v10
	v_mul_f32_e32 v7, v20, v11
	v_cvt_pk_bf16_f32 v6, v6, v7
	v_mul_f32_e32 v7, v20, v12
	v_mul_f32_e32 v8, v20, v13
	v_cvt_pk_bf16_f32 v7, v7, v8
	global_store_dwordx2 v[18:19], v[6:7], off offset:32
	v_mul_f32_e32 v6, v20, v14
	v_mul_f32_e32 v7, v20, v15
	v_cvt_pk_bf16_f32 v6, v6, v7
	v_mul_f32_e32 v7, v20, v16
	v_mul_f32_e32 v8, v20, v17
	v_cvt_pk_bf16_f32 v7, v7, v8
	global_store_dwordx2 v[18:19], v[6:7], off offset:64
	v_mul_f32_e32 v6, v20, v22
	v_mul_f32_e32 v7, v20, v23
	v_cvt_pk_bf16_f32 v6, v6, v7
	v_mul_f32_e32 v7, v20, v24
	v_mul_f32_e32 v8, v20, v25
	v_cvt_pk_bf16_f32 v7, v7, v8
	global_store_dwordx2 v[18:19], v[6:7], off offset:96
	v_mul_f32_e32 v6, v20, v26
	v_mul_f32_e32 v7, v20, v27
	v_cvt_pk_bf16_f32 v6, v6, v7
	v_mul_f32_e32 v7, v20, v28
	v_mul_f32_e32 v8, v20, v29
	v_cvt_pk_bf16_f32 v7, v7, v8
	global_store_dwordx2 v[18:19], v[6:7], off offset:128
	v_mul_f32_e32 v6, v20, v30
	v_mul_f32_e32 v7, v20, v31
	v_cvt_pk_bf16_f32 v6, v6, v7
	v_mul_f32_e32 v7, v20, v32
	v_mul_f32_e32 v8, v20, v33
	v_cvt_pk_bf16_f32 v7, v7, v8
	global_store_dwordx2 v[18:19], v[6:7], off offset:160
	v_mul_f32_e32 v6, v20, v34
	v_mul_f32_e32 v7, v20, v35
	v_cvt_pk_bf16_f32 v6, v6, v7
	v_mul_f32_e32 v7, v20, v36
	v_mul_f32_e32 v2, v20, v2
	v_mul_f32_e32 v3, v20, v3
	v_mul_f32_e32 v8, v20, v37
	v_cvt_pk_bf16_f32 v7, v7, v8
	global_store_dwordx2 v[18:19], v[6:7], off offset:192
	v_cvt_pk_bf16_f32 v2, v2, v3
	v_mul_f32_e32 v3, v20, v4
	v_mul_f32_e32 v4, v20, v5
	v_cvt_pk_bf16_f32 v3, v3, v4
	global_store_dwordx2 v[18:19], v[2:3], off offset:224
	s_waitcnt vmcnt(0)
	s_barrier
	s_cbranch_scc1 .LBB9_802
; #define LAS __attribute__((address_space(3)))
; #define ATT_KLOAD(buf, p) do { const bf16_t* kp_ = kloc + (size_t)((p) * 8 * NH) * 1024; \
;         _Pragma("unroll") for (int f = 0; f < 2; ++f) _Pragma("unroll") for (int ks = 0; ks < 4; ++ks) ka[buf][f * 4 + ks] = *(const bf16x8*)(kp_ + f * 128 + ks * 256); } while (0)
; template <bool LOCAL>
; __device__ __forceinline__ void attn_unit(const bf16_t* Q, const bf16_t* KT, const bf16_t* VT, bf16_t* O, LAS unsigned char* lds, int b, int h, int r, int w, int tq, int lane) {
;     const int g = lane >> 4, q = lane & 15;
;     const int qrow = LOCAL ? (b * SEQ + r * GRID_W + 16 * w + q) : (ML + b * CTX + 16 * tq + q);
;     bf16x8 bq[4];
;     { const bf16_t* qp = Q + (size_t)qrow * D + h * HD + 8 * g;
; #pragma unroll
;       for (int ks = 0; ks < 4; ++ks) bq[ks] = *(const bf16x8*)(qp + 32 * ks); }
;     constexpr int NP = LOCAL ? 16 : 8, CP = LOCAL ? 8 : 0;
;     f32x4 s[2 * NP];
;     int rs = 0, ws = 0;
;     if (LOCAL) { rs = r - 4; rs = rs < 0 ? 0 : (rs > 24 ? 24 : rs); ws = 16 * w - 8; ws = ws < 0 ? 0 : (ws > 32 ? 32 : ws); }
;     const int rgl = b * SEQ + rs * GRID_W + ws;
;     if (LOCAL) {
;         const bf16_t* kloc = KT + ((size_t)(((rgl >> 3) + (q >> 2)) * NH + h)) * 1024 + (q & 3) * 32 + g * 8;
;         bf16x8 ka[2][8];
;     ...
;         ATT_KLOAD(0, 0);
; #pragma unroll
;         for (int p = 0; p < 8; ++p) {
;             __builtin_amdgcn_s_barrier();
;             if (p + 1 < 8) ATT_KLOAD((p + 1) & 1, p + 1);
;             __builtin_amdgcn_sched_barrier(0);
.LBB9_674:
	v_ashrrev_i32_e32 v163, 31, v162
	v_lshlrev_b64 v[2:3], 12, v[162:163]
	s_mov_b32 s4, s52
	v_lshl_add_u64 v[2:3], v[158:159], 0, v[2:3]
	global_load_dwordx4 v[138:141], v[2:3], off
	global_load_dwordx4 v[134:137], v[2:3], off offset:64
	global_load_dwordx4 v[130:133], v[2:3], off offset:128
	global_load_dwordx4 v[62:65], v[2:3], off offset:192
	v_med3_i32 v2, s4, 4, 28
	v_lshlrev_b32_e32 v2, 6, v2
	v_add_u32_e32 v2, v2, v157
	v_add_u32_e32 v2, 0xffffff00, v2
	v_ashrrev_i32_e32 v194, 3, v2
	v_add_u32_e32 v2, v194, v168
	v_lshl_or_b32 v2, v2, 4, s72
	v_ashrrev_i32_e32 v3, 31, v2
	v_lshlrev_b64 v[2:3], 11, v[2:3]
	v_lshl_add_u64 v[70:71], v[146:147], 0, v[2:3]
	v_med3_i32 v232, s52, 4, 28
	v_add_u32_e32 v195, s51, v232
	s_lshr_b32 s54, s57, 2
	s_sub_i32 s54, s52, s54
	s_add_i32 s55, s54, -4
	s_max_i32 s55, s55, 0
	s_min_i32 s55, s55, 24
	s_add_i32 s73, s54, -3
	s_max_i32 s73, s73, 0
	s_min_i32 s73, s73, 24
	s_sub_i32 s73, s73, s55
	s_lshr_b32 s54, s57, 2
	s_mul_i32 s53, s73, s54
	s_ashr_i32 s54, s70, 6
	s_lshl_b32 s54, s54, 8
	s_lshl_b32 s55, s55, 3
	s_add_i32 s54, s54, s55
	s_add_i32 s54, s54, s57
	s_lshl_b32 s54, s54, 15
	s_lshl_b32 s55, s72, 11
	s_add_i32 s28, s54, s55
	s_mov_b32 s75, 0x200000
	s_lshl_b32 s54, s57, 10
	s_add_i32 s59, s54, 0x10000
	s_and_b32 s54, s57, 1
	s_lshl_b32 s54, s54, 1
	v_xor_b32_e32 v218, s54, v164
	v_lshlrev_b32_e32 v218, 4, v218
	v_add_u32_e32 v218, s28, v218
	ds_read_b64 v[220:221], v241 offset:192
	s_waitcnt lgkmcnt(0)
	v_add_co_u32_e32 v220, vcc, 0x21f00000, v220
	s_nop 1
	v_addc_co_u32_e32 v221, vcc, 0, v221, vcc
	v_add_co_u32_e32 v220, vcc, v220, v218
	s_nop 1
	v_addc_co_u32_e32 v221, vcc, 0, v221, vcc
	v_add_co_u32_e32 v226, vcc, 0x400, v220
	s_nop 1
	v_addc_co_u32_e32 v227, vcc, 0, v221, vcc
	s_and_b32 s55, s57, 3
	s_lshl_b32 s55, s55, 1
	s_add_i32 s55, s55, -1
	s_max_i32 s55, s55, 0
	s_min_i32 s55, s55, 4
	v_lshrrev_b32_e32 v219, 2, v166
	v_add_u32_e32 v219, s55, v219
	v_and_b32_e32 v224, 3, v166
	v_lshl_or_b32 v224, v224, 2, v165
	v_and_b32_e32 v225, 1, v219
	v_lshlrev_b32_e32 v225, 1, v225
	v_xor_b32_e32 v224, v224, v225
	v_lshlrev_b32_e32 v224, 4, v224
	v_lshl_add_u32 v219, v219, 10, v224
	v_add_u32_e32 v219, 0x10000, v219
	s_add_i32 m0, s59, 0
	s_nop 0
	global_load_lds_dwordx4 v[220:221], off
	s_add_i32 m0, s59, 8192
	s_nop 0
	global_load_lds_dwordx4 v[226:227], off
	s_add_i32 m0, s59, 16384
	v_add_co_u32_e32 v222, vcc, s6, v220
	s_nop 1
	v_addc_co_u32_e32 v223, vcc, 0, v221, vcc
	global_load_lds_dwordx4 v[222:223], off
	s_add_i32 m0, s59, 24576
	v_add_co_u32_e32 v222, vcc, s6, v226
	s_nop 1
	v_addc_co_u32_e32 v223, vcc, 0, v227, vcc
	global_load_lds_dwordx4 v[222:223], off
	s_add_i32 m0, s59, 32768
	v_add_co_u32_e32 v222, vcc, s7, v220
	s_nop 1
	v_addc_co_u32_e32 v223, vcc, 0, v221, vcc
	global_load_lds_dwordx4 v[222:223], off
	s_add_i32 m0, s59, 40960
	v_add_co_u32_e32 v222, vcc, s7, v226
	s_nop 1
	v_addc_co_u32_e32 v223, vcc, 0, v227, vcc
	global_load_lds_dwordx4 v[222:223], off
	s_add_i32 m0, s59, 49152
	v_add_co_u32_e32 v222, vcc, s2, v220
	s_nop 1
	v_addc_co_u32_e32 v223, vcc, 0, v221, vcc
	global_load_lds_dwordx4 v[222:223], off
	s_cmp_eq_u32 s53, 0
	s_cbranch_scc0 .Lrg_k_B
	s_waitcnt vmcnt(6)
	s_barrier
	s_add_i32 m0, s59, 57344
	v_add_co_u32_e32 v222, vcc, s2, v226
	s_nop 1
	v_addc_co_u32_e32 v223, vcc, 0, v227, vcc
	global_load_lds_dwordx4 v[222:223], off
	ds_read_b128 v[2:5], v219 offset:0
	ds_read_b128 v[6:9], v219 offset:256
	ds_read_b128 v[10:13], v219 offset:512
	ds_read_b128 v[14:17], v219 offset:768
	s_waitcnt lgkmcnt(3)
	v_mfma_f32_16x16x32_bf16 v[126:129], v[2:5], v[138:141], 0
	s_waitcnt lgkmcnt(2)
	v_mfma_f32_16x16x32_bf16 v[122:125], v[6:9], v[138:141], 0
	s_waitcnt lgkmcnt(1)
	v_mfma_f32_16x16x32_bf16 v[126:129], v[10:13], v[134:137], v[126:129]
	s_waitcnt lgkmcnt(0)
	v_mfma_f32_16x16x32_bf16 v[122:125], v[14:17], v[134:137], v[122:125]
	s_waitcnt vmcnt(6)
	s_barrier
	s_add_i32 m0, s59, 0
	v_add_co_u32_e32 v222, vcc, s60, v220
	s_nop 1
	v_addc_co_u32_e32 v223, vcc, 0, v221, vcc
	global_load_lds_dwordx4 v[222:223], off
	ds_read_b128 v[18:21], v219 offset:8192
	ds_read_b128 v[22:25], v219 offset:8448
	ds_read_b128 v[26:29], v219 offset:8704
	ds_read_b128 v[30:33], v219 offset:8960
	s_waitcnt lgkmcnt(3)
	v_mfma_f32_16x16x32_bf16 v[126:129], v[18:21], v[130:133], v[126:129]
	s_waitcnt lgkmcnt(2)
	v_mfma_f32_16x16x32_bf16 v[122:125], v[22:25], v[130:133], v[122:125]
	s_waitcnt lgkmcnt(1)
	v_mfma_f32_16x16x32_bf16 v[126:129], v[26:29], v[62:65], v[126:129]
	s_waitcnt lgkmcnt(0)
	v_mfma_f32_16x16x32_bf16 v[122:125], v[30:33], v[62:65], v[122:125]
	s_waitcnt vmcnt(6)
	s_barrier
; #define ATT_KLOAD(buf, p) do { const bf16_t* kp_ = kloc + (size_t)((p) * 8 * NH) * 1024; \
;         _Pragma("unroll") for (int f = 0; f < 2; ++f) _Pragma("unroll") for (int ks = 0; ks < 4; ++ks) ka[buf][f * 4 + ks] = *(const bf16x8*)(kp_ + f * 128 + ks * 256); } while (0)
; template <bool LOCAL>
; __device__ __forceinline__ void attn_unit(const bf16_t* Q, const bf16_t* KT, const bf16_t* VT, bf16_t* O, LAS unsigned char* lds, int b, int h, int r, int w, int tq, int lane) {
;     ...
;         for (int p = 0; p < 8; ++p) {
;             __builtin_amdgcn_s_barrier();
;             if (p + 1 < 8) ATT_KLOAD((p + 1) & 1, p + 1);
;             __builtin_amdgcn_sched_barrier(0);
; #pragma unroll
;             for (int f = 0; f < 2; ++f) { f32x4 a = {0.f, 0.f, 0.f, 0.f};
; #pragma unroll
;                 for (int ks = 0; ks < 4; ++ks) a = __builtin_amdgcn_mfma_f32_16x16x32_bf16(ka[p & 1][f * 4 + ks], bq[ks], a, 0, 0, 0);
;                 s[2 * p + f] = a; }
;             __builtin_amdgcn_sched_barrier(0);
;         }
	s_add_i32 m0, s59, 8192
	v_add_co_u32_e32 v222, vcc, s60, v226
	s_nop 1
	v_addc_co_u32_e32 v223, vcc, 0, v227, vcc
	global_load_lds_dwordx4 v[222:223], off
	ds_read_b128 v[2:5], v219 offset:16384
	ds_read_b128 v[6:9], v219 offset:16640
	ds_read_b128 v[10:13], v219 offset:16896
	ds_read_b128 v[14:17], v219 offset:17152
	s_waitcnt lgkmcnt(3)
	v_mfma_f32_16x16x32_bf16 v[118:121], v[2:5], v[138:141], 0
	s_waitcnt lgkmcnt(2)
	v_mfma_f32_16x16x32_bf16 v[114:117], v[6:9], v[138:141], 0
	s_waitcnt lgkmcnt(1)
	v_mfma_f32_16x16x32_bf16 v[118:121], v[10:13], v[134:137], v[118:121]
	s_waitcnt lgkmcnt(0)
	v_mfma_f32_16x16x32_bf16 v[114:117], v[14:17], v[134:137], v[114:117]
	s_waitcnt vmcnt(6)
	s_barrier
	s_add_i32 m0, s59, 16384
	v_add_co_u32_e32 v222, vcc, s61, v220
	s_nop 1
	v_addc_co_u32_e32 v223, vcc, 0, v221, vcc
	global_load_lds_dwordx4 v[222:223], off
	ds_read_b128 v[18:21], v219 offset:24576
	ds_read_b128 v[22:25], v219 offset:24832
	ds_read_b128 v[26:29], v219 offset:25088
	ds_read_b128 v[30:33], v219 offset:25344
	s_waitcnt lgkmcnt(3)
	v_mfma_f32_16x16x32_bf16 v[118:121], v[18:21], v[130:133], v[118:121]
	s_waitcnt lgkmcnt(2)
	v_mfma_f32_16x16x32_bf16 v[114:117], v[22:25], v[130:133], v[114:117]
	s_waitcnt lgkmcnt(1)
	v_mfma_f32_16x16x32_bf16 v[118:121], v[26:29], v[62:65], v[118:121]
	s_waitcnt lgkmcnt(0)
	v_mfma_f32_16x16x32_bf16 v[114:117], v[30:33], v[62:65], v[114:117]
	s_waitcnt vmcnt(6)
	s_barrier
	s_add_i32 m0, s59, 24576
	v_add_co_u32_e32 v222, vcc, s61, v226
	s_nop 1
	v_addc_co_u32_e32 v223, vcc, 0, v227, vcc
	global_load_lds_dwordx4 v[222:223], off
	ds_read_b128 v[2:5], v219 offset:32768
	ds_read_b128 v[6:9], v219 offset:33024
	ds_read_b128 v[10:13], v219 offset:33280
	ds_read_b128 v[14:17], v219 offset:33536
	s_waitcnt lgkmcnt(3)
	v_mfma_f32_16x16x32_bf16 v[110:113], v[2:5], v[138:141], 0
	s_waitcnt lgkmcnt(2)
	v_mfma_f32_16x16x32_bf16 v[106:109], v[6:9], v[138:141], 0
	s_waitcnt lgkmcnt(1)
	v_mfma_f32_16x16x32_bf16 v[110:113], v[10:13], v[134:137], v[110:113]
	s_waitcnt lgkmcnt(0)
	v_mfma_f32_16x16x32_bf16 v[106:109], v[14:17], v[134:137], v[106:109]
	s_waitcnt vmcnt(6)
	s_barrier
	s_add_i32 m0, s59, 32768
	v_add_co_u32_e32 v222, vcc, s17, v220
	s_nop 1
	v_addc_co_u32_e32 v223, vcc, 0, v221, vcc
	global_load_lds_dwordx4 v[222:223], off
	ds_read_b128 v[18:21], v219 offset:40960
	ds_read_b128 v[22:25], v219 offset:41216
	ds_read_b128 v[26:29], v219 offset:41472
	ds_read_b128 v[30:33], v219 offset:41728
	s_waitcnt lgkmcnt(3)
	v_mfma_f32_16x16x32_bf16 v[110:113], v[18:21], v[130:133], v[110:113]
	s_waitcnt lgkmcnt(2)
	v_mfma_f32_16x16x32_bf16 v[106:109], v[22:25], v[130:133], v[106:109]
	s_waitcnt lgkmcnt(1)
	v_mfma_f32_16x16x32_bf16 v[110:113], v[26:29], v[62:65], v[110:113]
	s_waitcnt lgkmcnt(0)
	v_mfma_f32_16x16x32_bf16 v[106:109], v[30:33], v[62:65], v[106:109]
	s_waitcnt vmcnt(6)
	s_barrier
	s_add_i32 m0, s59, 40960
	v_add_co_u32_e32 v222, vcc, s17, v226
	s_nop 1
	v_addc_co_u32_e32 v223, vcc, 0, v227, vcc
	global_load_lds_dwordx4 v[222:223], off
	ds_read_b128 v[2:5], v219 offset:49152
	ds_read_b128 v[6:9], v219 offset:49408
	ds_read_b128 v[10:13], v219 offset:49664
	ds_read_b128 v[14:17], v219 offset:49920
	s_waitcnt lgkmcnt(3)
	v_mfma_f32_16x16x32_bf16 v[102:105], v[2:5], v[138:141], 0
	s_waitcnt lgkmcnt(2)
	v_mfma_f32_16x16x32_bf16 v[98:101], v[6:9], v[138:141], 0
	s_waitcnt lgkmcnt(1)
	v_mfma_f32_16x16x32_bf16 v[102:105], v[10:13], v[134:137], v[102:105]
	s_waitcnt lgkmcnt(0)
	v_mfma_f32_16x16x32_bf16 v[98:101], v[14:17], v[134:137], v[98:101]
	s_waitcnt vmcnt(6)
	s_barrier
	s_add_i32 m0, s59, 49152
	v_add_co_u32_e32 v222, vcc, s62, v220
	s_nop 1
	v_addc_co_u32_e32 v223, vcc, 0, v221, vcc
	global_load_lds_dwordx4 v[222:223], off
	ds_read_b128 v[18:21], v219 offset:57344
	ds_read_b128 v[22:25], v219 offset:57600
	ds_read_b128 v[26:29], v219 offset:57856
	ds_read_b128 v[30:33], v219 offset:58112
	s_waitcnt lgkmcnt(3)
	v_mfma_f32_16x16x32_bf16 v[102:105], v[18:21], v[130:133], v[102:105]
	s_waitcnt lgkmcnt(2)
	v_mfma_f32_16x16x32_bf16 v[98:101], v[22:25], v[130:133], v[98:101]
	s_waitcnt lgkmcnt(1)
	v_mfma_f32_16x16x32_bf16 v[102:105], v[26:29], v[62:65], v[102:105]
	s_waitcnt lgkmcnt(0)
	v_mfma_f32_16x16x32_bf16 v[98:101], v[30:33], v[62:65], v[98:101]
	s_waitcnt vmcnt(6)
	s_barrier
	s_add_i32 m0, s59, 57344
	v_add_co_u32_e32 v222, vcc, s62, v226
	s_nop 1
	v_addc_co_u32_e32 v223, vcc, 0, v227, vcc
	global_load_lds_dwordx4 v[222:223], off
	ds_read_b128 v[2:5], v219 offset:0
	ds_read_b128 v[6:9], v219 offset:256
	ds_read_b128 v[10:13], v219 offset:512
	ds_read_b128 v[14:17], v219 offset:768
	s_waitcnt lgkmcnt(3)
	v_mfma_f32_16x16x32_bf16 v[94:97], v[2:5], v[138:141], 0
	s_waitcnt lgkmcnt(2)
	v_mfma_f32_16x16x32_bf16 v[90:93], v[6:9], v[138:141], 0
	s_waitcnt lgkmcnt(1)
	v_mfma_f32_16x16x32_bf16 v[94:97], v[10:13], v[134:137], v[94:97]
	s_waitcnt lgkmcnt(0)
	v_mfma_f32_16x16x32_bf16 v[90:93], v[14:17], v[134:137], v[90:93]
	s_waitcnt vmcnt(6)
	s_barrier
	s_cmp_eq_u32 s73, 0
	s_cbranch_scc1 .Lrg_k_A_nd9
	s_add_i32 m0, s59, 0
	v_add_co_u32_e32 v222, vcc, s75, v220
	s_nop 1
	v_addc_co_u32_e32 v223, vcc, 0, v221, vcc
	global_load_lds_dwordx4 v[222:223], off
